# v3 + L2 touch-prefetch of next chunk U columns in scan pass 2 + P0 GW-table build with all loads in flight
# speedup vs baseline: 1.0177x; 1.0058x over previous
.LBB0_19:
	v_lshrrev_b32_e32 v12, 3, v128
	v_lshlrev_b32_e32 v13, 2, v12
	v_mad_u64_u32 v[14:15], s[0:1], v12, s19, v[6:7]
	v_lshl_add_u64 v[14:15], v[14:15], 0, v[2:3]
	s_mov_b64 s[98:99], 0x2000
	v_lshl_add_u64 v[14:15], v[14:15], 0, s[98:99]
	s_mov_b64 s[98:99], 0x100800
	v_add_u32_e32 v16, 0x11000, v1
	global_load_dword v32, v13, s[64:65]
	global_load_dword v48, v[14:15], off
	v_lshl_add_u64 v[14:15], v[14:15], 0, s[98:99]
	global_load_dword v33, v13, s[64:65] offset:256
	global_load_dword v49, v[14:15], off
	v_lshl_add_u64 v[14:15], v[14:15], 0, s[98:99]
	global_load_dword v34, v13, s[64:65] offset:512
	global_load_dword v50, v[14:15], off
	v_lshl_add_u64 v[14:15], v[14:15], 0, s[98:99]
	global_load_dword v35, v13, s[64:65] offset:768
	global_load_dword v51, v[14:15], off
	v_lshl_add_u64 v[14:15], v[14:15], 0, s[98:99]
	global_load_dword v36, v13, s[64:65] offset:1024
	global_load_dword v52, v[14:15], off
	v_lshl_add_u64 v[14:15], v[14:15], 0, s[98:99]
	global_load_dword v37, v13, s[64:65] offset:1280
	global_load_dword v53, v[14:15], off
	v_lshl_add_u64 v[14:15], v[14:15], 0, s[98:99]
	global_load_dword v38, v13, s[64:65] offset:1536
	global_load_dword v54, v[14:15], off
	v_lshl_add_u64 v[14:15], v[14:15], 0, s[98:99]
	global_load_dword v39, v13, s[64:65] offset:1792
	global_load_dword v55, v[14:15], off
	v_lshl_add_u64 v[14:15], v[14:15], 0, s[98:99]
	global_load_dword v40, v13, s[64:65] offset:2048
	global_load_dword v56, v[14:15], off
	v_lshl_add_u64 v[14:15], v[14:15], 0, s[98:99]
	global_load_dword v41, v13, s[64:65] offset:2304
	global_load_dword v57, v[14:15], off
	v_lshl_add_u64 v[14:15], v[14:15], 0, s[98:99]
	global_load_dword v42, v13, s[64:65] offset:2560
	global_load_dword v58, v[14:15], off
	v_lshl_add_u64 v[14:15], v[14:15], 0, s[98:99]
	global_load_dword v43, v13, s[64:65] offset:2816
	global_load_dword v59, v[14:15], off
	v_lshl_add_u64 v[14:15], v[14:15], 0, s[98:99]
	global_load_dword v44, v13, s[64:65] offset:3072
	global_load_dword v60, v[14:15], off
	v_lshl_add_u64 v[14:15], v[14:15], 0, s[98:99]
	global_load_dword v45, v13, s[64:65] offset:3328
	global_load_dword v61, v[14:15], off
	v_lshl_add_u64 v[14:15], v[14:15], 0, s[98:99]
	global_load_dword v46, v13, s[64:65] offset:3584
	global_load_dword v62, v[14:15], off
	v_lshl_add_u64 v[14:15], v[14:15], 0, s[98:99]
	global_load_dword v47, v13, s[64:65] offset:3840
	global_load_dword v63, v[14:15], off
	s_mov_b32 s18, 16
	s_waitcnt vmcnt(0)
	v_mul_f32_e32 v32, v32, v48
	v_mul_f32_e32 v33, v33, v49
	v_mul_f32_e32 v34, v34, v50
	v_mul_f32_e32 v35, v35, v51
	v_mul_f32_e32 v36, v36, v52
	v_mul_f32_e32 v37, v37, v53
	v_mul_f32_e32 v38, v38, v54
	v_mul_f32_e32 v39, v39, v55
	v_mul_f32_e32 v40, v40, v56
	v_mul_f32_e32 v41, v41, v57
	v_mul_f32_e32 v42, v42, v58
	v_mul_f32_e32 v43, v43, v59
	v_mul_f32_e32 v44, v44, v60
	v_mul_f32_e32 v45, v45, v61
	v_mul_f32_e32 v46, v46, v62
	v_mul_f32_e32 v47, v47, v63
	ds_write_b32 v16, v32
	ds_write_b32 v16, v33 offset:2048
	ds_write_b32 v16, v34 offset:4096
	ds_write_b32 v16, v35 offset:6144
	ds_write_b32 v16, v36 offset:8192
	ds_write_b32 v16, v37 offset:10240
	ds_write_b32 v16, v38 offset:12288
	ds_write_b32 v16, v39 offset:14336
	ds_write_b32 v16, v40 offset:16384
	ds_write_b32 v16, v41 offset:18432
	ds_write_b32 v16, v42 offset:20480
	ds_write_b32 v16, v43 offset:22528
	ds_write_b32 v16, v44 offset:24576
	ds_write_b32 v16, v45 offset:26624
	ds_write_b32 v16, v46 offset:28672
	ds_write_b32 v16, v47 offset:30720
	s_or_b64 exec, exec, s[16:17]
	v_and_b32_e32 v3, 2, v10
	v_cmp_eq_u32_e32 vcc, 0, v3
	s_and_saveexec_b64 s[0:1], vcc
	s_cbranch_execz .LBB0_22
	v_lshrrev_b32_e32 v3, 3, v5
	v_lshrrev_b32_e32 v10, 3, v4
	s_movk_i32 s14, 0x4020
	v_mov_b64_e32 v[6:7], s[56:57]
	v_lshlrev_b32_e32 v4, 2, v10
	v_lshlrev_b32_e32 v5, 2, v3
	v_mad_u64_u32 v[10:11], s[16:17], v10, s14, v[6:7]
	v_mad_u64_u32 v[6:7], s[16:17], v3, s14, v[6:7]
	v_mov_b32_e32 v3, 0
	v_lshl_add_u64 v[10:11], v[10:11], 0, v[2:3]
	s_movk_i32 s14, 0x2000
	v_lshl_add_u64 v[2:3], v[6:7], 0, v[2:3]
	v_add_co_u32_e32 v6, vcc, s14, v10
	global_load_dword v4, v4, s[64:65]
	s_nop 0
	global_load_dword v5, v5, s[64:65]
	v_addc_co_u32_e32 v7, vcc, 0, v11, vcc
	v_add_co_u32_e32 v2, vcc, s14, v2
	s_nop 1
	v_addc_co_u32_e32 v3, vcc, 0, v3, vcc
	global_load_dword v6, v[6:7], off
	s_nop 0
	global_load_dword v7, v[2:3], off
	v_lshl_or_b32 v2, v9, 11, v1
	v_add_u32_e32 v9, 0, v2
	s_waitcnt vmcnt(0)
	v_pk_mul_f32 v[2:3], v[4:5], v[6:7]
	v_add_u32_e32 v4, 0x11000, v9
	ds_write2st64_b32 v4, v2, v3 offset1:8

.LBB0_767:
	v_and_b32_e32 v49, 12, v141
	v_bfe_u32 v50, v138, 2, 2
	v_bitop3_b32 v49, v49, v139, v50 bitop3:0x36
	v_lshlrev_b32_e32 v48, 8, v138
	v_lshlrev_b32_e32 v49, 4, v49
	v_add3_u32 v48, s83, v49, v48
	s_waitcnt vmcnt(3)
	ds_write_b128 v48, v[40:43]
	v_lshlrev_b32_e32 v41, 2, v140
	v_and_b32_e32 v41, 12, v41
	v_bfe_u32 v42, v140, 2, 2
	v_bitop3_b32 v41, v139, v41, v42 bitop3:0x1e
	v_lshlrev_b32_e32 v40, 8, v140
	v_lshlrev_b32_e32 v41, 4, v41
	v_add3_u32 v40, s83, v41, v40
	s_waitcnt vmcnt(2)
	ds_write_b128 v40, v[32:35]
	v_lshlrev_b32_e32 v33, 2, v142
	v_and_b32_e32 v33, 12, v33
	v_bfe_u32 v34, v142, 2, 2
	v_bitop3_b32 v33, v139, v33, v34 bitop3:0x1e
	v_lshlrev_b32_e32 v32, 8, v142
	v_lshlrev_b32_e32 v33, 4, v33
	v_add3_u32 v32, s83, v33, v32
	v_lshlrev_b32_e32 v33, 2, v144
	v_and_b32_e32 v33, 12, v33
	v_bfe_u32 v34, v144, 2, 2
	v_bitop3_b32 v33, v139, v33, v34 bitop3:0x1e
	v_and_b32_e32 v196, 3, v132
	s_waitcnt vmcnt(1)
	ds_write_b128 v32, v[44:47]
	v_lshlrev_b32_e32 v32, 8, v144
	v_lshlrev_b32_e32 v33, 4, v33
	v_ashrrev_i32_e32 v120, 2, v132
	v_add3_u32 v32, s83, v33, v32
	v_lshlrev_b32_e32 v40, 2, v196
	v_and_b32_e32 v41, 12, v132
	v_bfe_u32 v42, v120, 2, 2
	s_waitcnt vmcnt(0)
	ds_write_b128 v32, v[36:39]
	s_lshl_b64 s[98:99], s[66:67], 13
	s_add_u32 s98, s98, s52
	s_addc_u32 s99, s99, s53
	s_mov_b32 m0, 0x22a00
	v_lshlrev_b32_e32 v36, 11, v128
	v_and_b32_e32 v36, 0xffffe000, v36
	global_load_lds_dword v36, s[98:99] offset:3072
	global_load_lds_dword v36, s[98:99] offset:3200
	s_cmp_eq_u32 s63, s75
	s_cbranch_scc1 .Lp3_touch_done
	s_add_u32 s98, s98, 0x100000
	s_addc_u32 s99, s99, 0
	global_load_lds_dword v36, s[98:99]
	global_load_lds_dword v36, s[98:99] offset:128
	global_load_lds_dword v36, s[98:99] offset:1024
	global_load_lds_dword v36, s[98:99] offset:1152
	global_load_lds_dword v36, s[98:99] offset:2048
	global_load_lds_dword v36, s[98:99] offset:2176
	global_load_lds_dword v36, s[98:99] offset:3072
	global_load_lds_dword v36, s[98:99] offset:3200
.Lp3_touch_done:
	v_bitop3_b32 v32, v42, v40, v41 bitop3:0x36
	v_lshl_add_u32 v43, v120, 8, 0
	v_lshlrev_b32_e32 v32, 4, v32
	s_waitcnt lgkmcnt(0)
	s_barrier
	v_add_u32_e32 v191, v43, v32
	ds_read_b128 v[32:35], v191
	v_or_b32_e32 v195, 1, v40
	v_or_b32_e32 v194, 2, v40
	v_or_b32_e32 v193, 3, v40
	v_lshl_add_u32 v40, v193, 5, s84
	s_waitcnt lgkmcnt(0)
	v_lshlrev_b32_e32 v44, 16, v32
	v_and_b32_e32 v45, 0xffff0000, v32
	v_lshl_add_u32 v32, v196, 7, s84
	ds_read_b128 v[36:39], v32
	v_lshlrev_b32_e32 v46, 16, v33
	v_and_b32_e32 v47, 0xffff0000, v33
	v_lshlrev_b32_e32 v48, 16, v34
	v_and_b32_e32 v49, 0xffff0000, v34
	v_lshlrev_b32_e32 v50, 16, v35
	v_and_b32_e32 v51, 0xffff0000, v35
	ds_read_b128 v[32:35], v32 offset:16
	s_waitcnt lgkmcnt(1)
	v_fma_f32 v44, v36, v44, 0
	v_fmac_f32_e32 v44, v37, v45
	v_fmac_f32_e32 v44, v38, v46
	v_fmac_f32_e32 v44, v39, v47
	s_waitcnt lgkmcnt(0)
	v_fmac_f32_e32 v44, v32, v48
	v_bitop3_b32 v32, v42, v195, v41 bitop3:0x36
	v_lshlrev_b32_e32 v32, 4, v32
	v_fmac_f32_e32 v44, v33, v49
	v_add_u32_e32 v190, v43, v32
	ds_read_b128 v[36:39], v190
	v_fmac_f32_e32 v44, v34, v50
	v_lshl_add_u32 v45, v195, 5, s84
	v_fmac_f32_e32 v44, v35, v51
	ds_read_b128 v[32:35], v45
	s_waitcnt lgkmcnt(1)
	v_lshlrev_b32_e32 v46, 16, v36
	v_and_b32_e32 v47, 0xffff0000, v36
	v_lshlrev_b32_e32 v48, 16, v37
	v_and_b32_e32 v49, 0xffff0000, v37
	v_lshlrev_b32_e32 v50, 16, v38
	v_and_b32_e32 v51, 0xffff0000, v38
	v_lshlrev_b32_e32 v52, 16, v39
	v_and_b32_e32 v53, 0xffff0000, v39
	ds_read_b128 v[36:39], v45 offset:16
	s_waitcnt lgkmcnt(1)
	v_fmac_f32_e32 v44, v32, v46
	v_bitop3_b32 v32, v42, v194, v41 bitop3:0x36
	v_fmac_f32_e32 v44, v33, v47
	v_lshlrev_b32_e32 v32, 4, v32
	v_fmac_f32_e32 v44, v34, v48
	v_add_u32_e32 v161, v43, v32
	v_fmac_f32_e32 v44, v35, v49
	ds_read_b128 v[32:35], v161
	s_waitcnt lgkmcnt(1)
	v_fmac_f32_e32 v44, v36, v50
	v_fmac_f32_e32 v44, v37, v51
	v_fmac_f32_e32 v44, v38, v52
	v_fmac_f32_e32 v44, v39, v53
	s_waitcnt lgkmcnt(0)
	v_lshlrev_b32_e32 v45, 16, v32
	v_and_b32_e32 v46, 0xffff0000, v32
	v_lshl_add_u32 v32, v194, 5, s84
	ds_read_b128 v[36:39], v32
	v_lshlrev_b32_e32 v47, 16, v33
	v_and_b32_e32 v48, 0xffff0000, v33
	v_lshlrev_b32_e32 v49, 16, v34
	v_and_b32_e32 v50, 0xffff0000, v34
	v_lshlrev_b32_e32 v51, 16, v35
	v_and_b32_e32 v52, 0xffff0000, v35
	ds_read_b128 v[32:35], v32 offset:16
	s_waitcnt lgkmcnt(1)
	v_fmac_f32_e32 v44, v36, v45
	v_fmac_f32_e32 v44, v37, v46
	v_fmac_f32_e32 v44, v38, v47
	v_fmac_f32_e32 v44, v39, v48
	s_waitcnt lgkmcnt(0)
	v_fmac_f32_e32 v44, v32, v49
	v_bitop3_b32 v32, v42, v193, v41 bitop3:0x36
	v_lshlrev_b32_e32 v32, 4, v32
	v_fmac_f32_e32 v44, v33, v50
	v_add_u32_e32 v117, v43, v32
	ds_read_b128 v[36:39], v117
	v_fmac_f32_e32 v44, v34, v51
	v_fmac_f32_e32 v44, v35, v52
	ds_read_b128 v[32:35], v40
	v_lshl_add_u32 v192, v120, 2, 0
	s_waitcnt lgkmcnt(1)
	v_lshlrev_b32_e32 v41, 16, v36
	v_and_b32_e32 v42, 0xffff0000, v36
	v_lshlrev_b32_e32 v43, 16, v37
	v_and_b32_e32 v45, 0xffff0000, v37
	v_lshlrev_b32_e32 v46, 16, v38
	v_and_b32_e32 v47, 0xffff0000, v38
	v_lshlrev_b32_e32 v48, 16, v39
	v_and_b32_e32 v49, 0xffff0000, v39
	ds_read_b128 v[36:39], v40 offset:16
	s_waitcnt lgkmcnt(1)
	v_fmac_f32_e32 v44, v32, v41
	v_fmac_f32_e32 v44, v33, v42
	v_fmac_f32_e32 v44, v34, v43
	v_fmac_f32_e32 v44, v35, v45
	v_and_b32_e32 v33, 64, v131
	v_mov_b32_e32 v34, s80
	v_xor_b32_e32 v32, 1, v131
	v_add_u32_e32 v33, 64, v33
	ds_read_b64 v[108:109], v34
	s_waitcnt lgkmcnt(1)
	v_fmac_f32_e32 v44, v36, v46
	v_fmac_f32_e32 v44, v37, v47
	v_cmp_lt_i32_e32 vcc, v32, v33
	v_fmac_f32_e32 v44, v38, v48
	v_fmac_f32_e32 v44, v39, v49
	v_cndmask_b32_e32 v32, v131, v32, vcc
	v_lshlrev_b32_e32 v197, 2, v32
	ds_bpermute_b32 v32, v197, v44
	v_xor_b32_e32 v34, 2, v131
	v_cmp_lt_i32_e32 vcc, v34, v33
	s_waitcnt lgkmcnt(0)
	v_add_f32_e32 v32, v44, v32
	v_cndmask_b32_e32 v33, v131, v34, vcc
	v_lshlrev_b32_e32 v198, 2, v33
	ds_bpermute_b32 v33, v198, v32
	v_cmp_eq_u32_e32 vcc, 0, v196
	s_and_saveexec_b64 s[0:1], vcc
	s_cbranch_execz .LBB0_769
	s_waitcnt lgkmcnt(0)
	v_add_f32_e32 v32, v32, v33
	v_add_u32_e32 v33, 0x20a00, v192
	ds_write_b32 v33, v32
